# grid barrier cross-XCD stage: per-XCD flag counters replicated per polling XCD (leader adds with one 8-lane atomic, all workgroups poll own replica) replacing TOP atomic-return + XGEN release; on top
# baseline (speedup 1.0000x reference)
; __device__ __forceinline__ unsigned xb_ld(unsigned* p)              { return __hip_atomic_load(p, __ATOMIC_RELAXED, __HIP_MEMORY_SCOPE_AGENT); }
; __device__ __forceinline__ unsigned xb_add(unsigned* p, unsigned v) { return __hip_atomic_fetch_add(p, v, __ATOMIC_RELAXED, __HIP_MEMORY_SCOPE_AGENT); }
; #define XB_SPIN(cond, bar) do { unsigned _sp = 0; while (cond) { __builtin_amdgcn_s_sleep(1); \
;     if ((++_sp & 255u) == 0u) { if (xb_ld(&(bar)[XB_TMO])) break; if (_sp > XB_SPIN_CAP) { atomicAdd(&(bar)[XB_TMO], 1u); break; } } } } while (0)
; __device__ __forceinline__ void xcd_barrier(const XcdBarrier& b) {
;     ...
;         const unsigned old = xb_add(&bar[XB_XSUB(b.x)], 1u);
;         const unsigned gen = old / nloc;
;         if (old + 1u == (gen + 1u) * nloc) {
;             __builtin_amdgcn_fence(__ATOMIC_RELEASE, "agent");
;             asm volatile("s_waitcnt vmcnt(0)" ::: "memory");
;             const unsigned og = xb_add(&bar[XB_TOP], 1u);
;             const unsigned tg = og / nx;
;             if (og + 1u != (tg + 1u) * nx) XB_SPIN(xb_ld(&bar[XB_TOP]) < (tg + 1u) * nx, bar);
;             __builtin_amdgcn_fence(__ATOMIC_ACQUIRE, "agent");
;             xb_add(&bar[XB_XGEN(b.x)], 1u);
;             asm volatile("s_waitcnt vmcnt(0)" ::: "memory");
;         } else {
;             XB_SPIN(xb_ld(&bar[XB_XGEN(b.x)]) == gen, bar);
;             __builtin_amdgcn_fence(__ATOMIC_ACQUIRE, "agent");
;             asm volatile("s_waitcnt vmcnt(0)" ::: "memory");
;         }
.LBB0_240:
	s_or_b64 exec, exec, s[6:7]
	v_cvt_f32_u32_e32 v4, v2
	s_waitcnt vmcnt(0)
	v_readfirstlane_b32 s4, v3
	v_sub_u32_e32 v3, 0, v2
	v_rcp_iflag_f32_e32 v4, v4
	v_add_u32_e32 v5, s4, v1
	v_mul_f32_e32 v4, 0x4f7ffffe, v4
	v_cvt_u32_f32_e32 v4, v4
	v_mul_lo_u32 v1, v3, v4
	v_mul_hi_u32 v1, v4, v1
	v_add_u32_e32 v1, v4, v1
	v_mul_hi_u32 v1, v5, v1
	v_mul_lo_u32 v3, v1, v2
	v_sub_u32_e32 v3, v5, v3
	v_add_u32_e32 v4, 1, v1
	v_cmp_ge_u32_e32 vcc, v3, v2
	s_nop 1
	v_cndmask_b32_e32 v1, v1, v4, vcc
	v_sub_u32_e32 v4, v3, v2
	v_cndmask_b32_e32 v3, v3, v4, vcc
	v_add_u32_e32 v4, 1, v1
	v_cmp_ge_u32_e32 vcc, v3, v2
	v_add_u32_e32 v3, 1, v5
	s_nop 0
	v_cndmask_b32_e32 v1, v1, v4, vcc
	v_mul_lo_u32 v4, v2, v1
	v_add_u32_e32 v2, v4, v2
	v_cmp_ne_u32_e32 vcc, v3, v2
	s_mov_b64 s[4:5], exec
	s_waitcnt lgkmcnt(0)
	v_readfirstlane_b32 s14, v1
	v_readfirstlane_b32 s15, v0
	s_and_b32 s6, s97, 7
	s_lshl_b32 s6, s6, 8
	s_add_u32 s6, s92, s6
	s_addc_u32 s7, s93, 0
	s_add_u32 s6, s6, 0x3800
	s_addc_u32 s7, s7, 0
	s_add_u32 s14, s14, 1
	s_cbranch_vccnz .Lxb0_poll
	buffer_wbl2 sc1
	s_waitcnt vmcnt(0)
	s_lshl_b32 s12, s97, 2
	s_add_u32 s12, s92, s12
	s_addc_u32 s13, s93, 0
	s_add_u32 s12, s12, 0x3800
	s_addc_u32 s13, s13, 0
	s_mov_b64 exec, 0xff
	v_mbcnt_lo_u32_b32 v240, -1, 0
	v_lshlrev_b32_e32 v240, 8, v240
	v_mov_b32_e32 v241, 1
	global_atomic_add v240, v241, s[12:13]
	s_nop 1
.Lxb0_poll:
	s_mov_b64 exec, 0xffff
	v_mbcnt_lo_u32_b32 v240, -1, 0
	v_lshlrev_b32_e32 v240, 2, v240
	s_mov_b32 s17, 0
.Lxb0_loop:
	global_load_dword v241, v240, s[6:7] sc1
	s_waitcnt vmcnt(0)
	v_cmp_le_u32_e32 vcc, s14, v241
	s_nop 0
	s_bcnt1_i32_b64 s16, vcc
	s_cmp_ge_u32 s16, s15
	s_cbranch_scc1 .Lxb0_done
	s_add_u32 s17, s17, 1
	s_cmp_lt_u32 s17, 0x4000
	s_cbranch_scc0 .Lxb0_done
	s_sleep 1
	s_branch .Lxb0_loop
.Lxb0_done:
	s_mov_b64 exec, s[4:5]
	buffer_inv sc1
	s_waitcnt vmcnt(0)

; __device__ __forceinline__ unsigned xb_ld(unsigned* p)              { return __hip_atomic_load(p, __ATOMIC_RELAXED, __HIP_MEMORY_SCOPE_AGENT); }
; __device__ __forceinline__ unsigned xb_add(unsigned* p, unsigned v) { return __hip_atomic_fetch_add(p, v, __ATOMIC_RELAXED, __HIP_MEMORY_SCOPE_AGENT); }
; #define XB_SPIN(cond, bar) do { unsigned _sp = 0; while (cond) { __builtin_amdgcn_s_sleep(1); \
;     if ((++_sp & 255u) == 0u) { if (xb_ld(&(bar)[XB_TMO])) break; if (_sp > XB_SPIN_CAP) { atomicAdd(&(bar)[XB_TMO], 1u); break; } } } } while (0)
; __device__ __forceinline__ void xcd_barrier(const XcdBarrier& b) {
;     ...
;         const unsigned old = xb_add(&bar[XB_XSUB(b.x)], 1u);
;         const unsigned gen = old / nloc;
;         if (old + 1u == (gen + 1u) * nloc) {
;             __builtin_amdgcn_fence(__ATOMIC_RELEASE, "agent");
;             asm volatile("s_waitcnt vmcnt(0)" ::: "memory");
;             const unsigned og = xb_add(&bar[XB_TOP], 1u);
;             const unsigned tg = og / nx;
;             if (og + 1u != (tg + 1u) * nx) XB_SPIN(xb_ld(&bar[XB_TOP]) < (tg + 1u) * nx, bar);
;             __builtin_amdgcn_fence(__ATOMIC_ACQUIRE, "agent");
;             xb_add(&bar[XB_XGEN(b.x)], 1u);
;             asm volatile("s_waitcnt vmcnt(0)" ::: "memory");
;         } else {
;             XB_SPIN(xb_ld(&bar[XB_XGEN(b.x)]) == gen, bar);
;             __builtin_amdgcn_fence(__ATOMIC_ACQUIRE, "agent");
;             asm volatile("s_waitcnt vmcnt(0)" ::: "memory");
;         }
.LBB0_321:
	s_or_b64 exec, exec, s[6:7]
	v_cvt_f32_u32_e32 v4, v2
	s_waitcnt vmcnt(0)
	v_readfirstlane_b32 s4, v3
	v_sub_u32_e32 v3, 0, v2
	v_rcp_iflag_f32_e32 v4, v4
	v_add_u32_e32 v5, s4, v1
	v_mul_f32_e32 v4, 0x4f7ffffe, v4
	v_cvt_u32_f32_e32 v4, v4
	v_mul_lo_u32 v1, v3, v4
	v_mul_hi_u32 v1, v4, v1
	v_add_u32_e32 v1, v4, v1
	v_mul_hi_u32 v1, v5, v1
	v_mul_lo_u32 v3, v1, v2
	v_sub_u32_e32 v3, v5, v3
	v_add_u32_e32 v4, 1, v1
	v_cmp_ge_u32_e32 vcc, v3, v2
	s_nop 1
	v_cndmask_b32_e32 v1, v1, v4, vcc
	v_sub_u32_e32 v4, v3, v2
	v_cndmask_b32_e32 v3, v3, v4, vcc
	v_add_u32_e32 v4, 1, v1
	v_cmp_ge_u32_e32 vcc, v3, v2
	v_add_u32_e32 v3, 1, v5
	s_nop 0
	v_cndmask_b32_e32 v1, v1, v4, vcc
	v_mul_lo_u32 v4, v2, v1
	v_add_u32_e32 v2, v4, v2
	v_cmp_ne_u32_e32 vcc, v3, v2
	s_mov_b64 s[4:5], exec
	s_waitcnt lgkmcnt(0)
	v_readfirstlane_b32 s16, v1
	v_readfirstlane_b32 s17, v0
	s_and_b32 s6, s97, 7
	s_lshl_b32 s6, s6, 8
	s_add_u32 s6, s92, s6
	s_addc_u32 s7, s93, 0
	s_add_u32 s6, s6, 0x3800
	s_addc_u32 s7, s7, 0
	s_add_u32 s16, s16, 1
	s_cbranch_vccnz .Lxb1_poll
	buffer_wbl2 sc1
	s_waitcnt vmcnt(0)
	s_lshl_b32 s12, s97, 2
	s_add_u32 s12, s92, s12
	s_addc_u32 s13, s93, 0
	s_add_u32 s12, s12, 0x3800
	s_addc_u32 s13, s13, 0
	s_mov_b64 exec, 0xff
	v_mbcnt_lo_u32_b32 v240, -1, 0
	v_lshlrev_b32_e32 v240, 8, v240
	v_mov_b32_e32 v241, 1
	global_atomic_add v240, v241, s[12:13]
	s_nop 1
.Lxb1_poll:
	s_mov_b64 exec, 0xffff
	v_mbcnt_lo_u32_b32 v240, -1, 0
	v_lshlrev_b32_e32 v240, 2, v240
	s_mov_b32 s19, 0
.Lxb1_loop:
	global_load_dword v241, v240, s[6:7] sc1
	s_waitcnt vmcnt(0)
	v_cmp_le_u32_e32 vcc, s16, v241
	s_nop 0
	s_bcnt1_i32_b64 s18, vcc
	s_cmp_ge_u32 s18, s17
	s_cbranch_scc1 .Lxb1_done
	s_add_u32 s19, s19, 1
	s_cmp_lt_u32 s19, 0x4000
	s_cbranch_scc0 .Lxb1_done
	s_sleep 1
	s_branch .Lxb1_loop

; __device__ __forceinline__ unsigned xb_add(unsigned* p, unsigned v) { return __hip_atomic_fetch_add(p, v, __ATOMIC_RELAXED, __HIP_MEMORY_SCOPE_AGENT); }
; __device__ __forceinline__ void xcd_barrier(const XcdBarrier& b) {
;     ...
;         const unsigned old = xb_add(&bar[XB_XSUB(b.x)], 1u);
;         const unsigned gen = old / nloc;
;         if (old + 1u == (gen + 1u) * nloc) {
;             __builtin_amdgcn_fence(__ATOMIC_RELEASE, "agent");
;             asm volatile("s_waitcnt vmcnt(0)" ::: "memory");
;             const unsigned og = xb_add(&bar[XB_TOP], 1u);
.LBB0_385:
	s_or_b64 exec, exec, s[10:11]
	v_cvt_f32_u32_e32 v4, v2
	s_waitcnt vmcnt(0)
	v_readfirstlane_b32 s6, v3
	v_sub_u32_e32 v3, 0, v2
	v_rcp_iflag_f32_e32 v4, v4
	v_add_u32_e32 v5, s6, v1
	v_mul_f32_e32 v4, 0x4f7ffffe, v4
	v_cvt_u32_f32_e32 v4, v4
	v_mul_lo_u32 v1, v3, v4
	v_mul_hi_u32 v1, v4, v1
	v_add_u32_e32 v1, v4, v1
	v_mul_hi_u32 v1, v5, v1
	v_mul_lo_u32 v3, v1, v2
	v_sub_u32_e32 v3, v5, v3
	v_add_u32_e32 v4, 1, v1
	v_cmp_ge_u32_e32 vcc, v3, v2
	s_nop 1
	v_cndmask_b32_e32 v1, v1, v4, vcc
	v_sub_u32_e32 v4, v3, v2
	v_cndmask_b32_e32 v3, v3, v4, vcc
	v_add_u32_e32 v4, 1, v1
	v_cmp_ge_u32_e32 vcc, v3, v2
	v_add_u32_e32 v3, 1, v5
	s_nop 0
	v_cndmask_b32_e32 v1, v1, v4, vcc
	v_mul_lo_u32 v4, v2, v1
	v_add_u32_e32 v2, v4, v2
	v_cmp_ne_u32_e32 vcc, v3, v2
	s_mov_b64 s[6:7], exec
	s_waitcnt lgkmcnt(0)
	v_readfirstlane_b32 s16, v1
	v_readfirstlane_b32 s17, v0
	s_and_b32 s10, s97, 7
	s_lshl_b32 s10, s10, 8
	s_add_u32 s10, s92, s10
	s_addc_u32 s11, s93, 0
	s_add_u32 s10, s10, 0x3800
	s_addc_u32 s11, s11, 0
	s_add_u32 s16, s16, 1
	s_cbranch_vccnz .Lxb2_poll
	buffer_wbl2 sc1
	s_waitcnt vmcnt(0)
	s_lshl_b32 s12, s97, 2
	s_add_u32 s12, s92, s12
	s_addc_u32 s13, s93, 0
	s_add_u32 s12, s12, 0x3800
	s_addc_u32 s13, s13, 0
	s_mov_b64 exec, 0xff
	v_mbcnt_lo_u32_b32 v240, -1, 0
	v_lshlrev_b32_e32 v240, 8, v240
	v_mov_b32_e32 v241, 1
	global_atomic_add v240, v241, s[12:13]
	s_nop 1

; __device__ __forceinline__ unsigned xb_ld(unsigned* p)              { return __hip_atomic_load(p, __ATOMIC_RELAXED, __HIP_MEMORY_SCOPE_AGENT); }
; __device__ __forceinline__ unsigned xb_add(unsigned* p, unsigned v) { return __hip_atomic_fetch_add(p, v, __ATOMIC_RELAXED, __HIP_MEMORY_SCOPE_AGENT); }
; #define XB_SPIN(cond, bar) do { unsigned _sp = 0; while (cond) { __builtin_amdgcn_s_sleep(1); \
;     if ((++_sp & 255u) == 0u) { if (xb_ld(&(bar)[XB_TMO])) break; if (_sp > XB_SPIN_CAP) { atomicAdd(&(bar)[XB_TMO], 1u); break; } } } } while (0)
; __device__ __forceinline__ void xcd_barrier(const XcdBarrier& b) {
;     ...
;             const unsigned tg = og / nx;
;             if (og + 1u != (tg + 1u) * nx) XB_SPIN(xb_ld(&bar[XB_TOP]) < (tg + 1u) * nx, bar);
;             __builtin_amdgcn_fence(__ATOMIC_ACQUIRE, "agent");
;             xb_add(&bar[XB_XGEN(b.x)], 1u);
;             asm volatile("s_waitcnt vmcnt(0)" ::: "memory");
;         } else {
;             XB_SPIN(xb_ld(&bar[XB_XGEN(b.x)]) == gen, bar);
;             __builtin_amdgcn_fence(__ATOMIC_ACQUIRE, "agent");
;             asm volatile("s_waitcnt vmcnt(0)" ::: "memory");
;         }
.Lxb2_loop:
	global_load_dword v241, v240, s[10:11] sc1
	s_waitcnt vmcnt(0)
	v_cmp_le_u32_e32 vcc, s16, v241
	s_nop 0
	s_bcnt1_i32_b64 s18, vcc
	s_cmp_ge_u32 s18, s17
	s_cbranch_scc1 .Lxb2_done
	s_add_u32 s19, s19, 1
	s_cmp_lt_u32 s19, 0x4000
	s_cbranch_scc0 .Lxb2_done
	s_sleep 1
	s_branch .Lxb2_loop
.Lxb2_done:
	s_mov_b64 exec, s[6:7]
	buffer_inv sc1
	s_waitcnt vmcnt(0)

; __device__ __forceinline__ unsigned xb_ld(unsigned* p)              { return __hip_atomic_load(p, __ATOMIC_RELAXED, __HIP_MEMORY_SCOPE_AGENT); }
; __device__ __forceinline__ unsigned xb_add(unsigned* p, unsigned v) { return __hip_atomic_fetch_add(p, v, __ATOMIC_RELAXED, __HIP_MEMORY_SCOPE_AGENT); }
; #define XB_SPIN(cond, bar) do { unsigned _sp = 0; while (cond) { __builtin_amdgcn_s_sleep(1); \
;     if ((++_sp & 255u) == 0u) { if (xb_ld(&(bar)[XB_TMO])) break; if (_sp > XB_SPIN_CAP) { atomicAdd(&(bar)[XB_TMO], 1u); break; } } } } while (0)
; __device__ __forceinline__ void xcd_barrier(const XcdBarrier& b) {
;     ...
;         const unsigned old = xb_add(&bar[XB_XSUB(b.x)], 1u);
;         const unsigned gen = old / nloc;
;         if (old + 1u == (gen + 1u) * nloc) {
;             __builtin_amdgcn_fence(__ATOMIC_RELEASE, "agent");
;             asm volatile("s_waitcnt vmcnt(0)" ::: "memory");
;             const unsigned og = xb_add(&bar[XB_TOP], 1u);
;             const unsigned tg = og / nx;
;             if (og + 1u != (tg + 1u) * nx) XB_SPIN(xb_ld(&bar[XB_TOP]) < (tg + 1u) * nx, bar);
;             __builtin_amdgcn_fence(__ATOMIC_ACQUIRE, "agent");
;             xb_add(&bar[XB_XGEN(b.x)], 1u);
;             asm volatile("s_waitcnt vmcnt(0)" ::: "memory");
;         } else {
;             XB_SPIN(xb_ld(&bar[XB_XGEN(b.x)]) == gen, bar);
;             __builtin_amdgcn_fence(__ATOMIC_ACQUIRE, "agent");
;             asm volatile("s_waitcnt vmcnt(0)" ::: "memory");
;         }
.LBB0_449:
	s_or_b64 exec, exec, s[12:13]
	v_cvt_f32_u32_e32 v4, v2
	s_waitcnt vmcnt(0)
	v_readfirstlane_b32 s6, v3
	v_sub_u32_e32 v3, 0, v2
	v_rcp_iflag_f32_e32 v4, v4
	v_add_u32_e32 v5, s6, v1
	v_mul_f32_e32 v4, 0x4f7ffffe, v4
	v_cvt_u32_f32_e32 v4, v4
	v_mul_lo_u32 v1, v3, v4
	v_mul_hi_u32 v1, v4, v1
	v_add_u32_e32 v1, v4, v1
	v_mul_hi_u32 v1, v5, v1
	v_mul_lo_u32 v3, v1, v2
	v_sub_u32_e32 v3, v5, v3
	v_add_u32_e32 v4, 1, v1
	v_cmp_ge_u32_e32 vcc, v3, v2
	s_nop 1
	v_cndmask_b32_e32 v1, v1, v4, vcc
	v_sub_u32_e32 v4, v3, v2
	v_cndmask_b32_e32 v3, v3, v4, vcc
	v_add_u32_e32 v4, 1, v1
	v_cmp_ge_u32_e32 vcc, v3, v2
	v_add_u32_e32 v3, 1, v5
	s_nop 0
	v_cndmask_b32_e32 v1, v1, v4, vcc
	v_mul_lo_u32 v4, v2, v1
	v_add_u32_e32 v2, v4, v2
	v_cmp_ne_u32_e32 vcc, v3, v2
	s_mov_b64 s[6:7], exec
	s_waitcnt lgkmcnt(0)
	v_readfirstlane_b32 s18, v1
	v_readfirstlane_b32 s19, v0
	s_and_b32 s12, s97, 7
	s_lshl_b32 s12, s12, 8
	s_add_u32 s12, s92, s12
	s_addc_u32 s13, s93, 0
	s_add_u32 s12, s12, 0x3800
	s_addc_u32 s13, s13, 0
	s_add_u32 s18, s18, 1
	s_cbranch_vccnz .Lxb3_poll
	buffer_wbl2 sc1
	s_waitcnt vmcnt(0)
	s_lshl_b32 s16, s97, 2
	s_add_u32 s16, s92, s16
	s_addc_u32 s17, s93, 0
	s_add_u32 s16, s16, 0x3800
	s_addc_u32 s17, s17, 0
	s_mov_b64 exec, 0xff
	v_mbcnt_lo_u32_b32 v240, -1, 0
	v_lshlrev_b32_e32 v240, 8, v240
	v_mov_b32_e32 v241, 1
	global_atomic_add v240, v241, s[16:17]
	s_nop 1
.Lxb3_poll:
	s_mov_b64 exec, 0xffff
	v_mbcnt_lo_u32_b32 v240, -1, 0
	v_lshlrev_b32_e32 v240, 2, v240
	s_mov_b32 s21, 0
.Lxb3_loop:
	global_load_dword v241, v240, s[12:13] sc1
	s_waitcnt vmcnt(0)
	v_cmp_le_u32_e32 vcc, s18, v241
	s_nop 0
	s_bcnt1_i32_b64 s20, vcc
	s_cmp_ge_u32 s20, s19
	s_cbranch_scc1 .Lxb3_done
	s_add_u32 s21, s21, 1
	s_cmp_lt_u32 s21, 0x4000
	s_cbranch_scc0 .Lxb3_done
	s_sleep 1
	s_branch .Lxb3_loop

; __device__ __forceinline__ unsigned xb_add(unsigned* p, unsigned v) { return __hip_atomic_fetch_add(p, v, __ATOMIC_RELAXED, __HIP_MEMORY_SCOPE_AGENT); }
; __device__ __forceinline__ void xcd_barrier(const XcdBarrier& b) {
;     ...
;         const unsigned old = xb_add(&bar[XB_XSUB(b.x)], 1u);
;         const unsigned gen = old / nloc;
;         if (old + 1u == (gen + 1u) * nloc) {
;             __builtin_amdgcn_fence(__ATOMIC_RELEASE, "agent");
;             asm volatile("s_waitcnt vmcnt(0)" ::: "memory");
;             const unsigned og = xb_add(&bar[XB_TOP], 1u);
.LBB0_537:
	s_or_b64 exec, exec, s[6:7]
	v_cvt_f32_u32_e32 v4, v2
	s_waitcnt vmcnt(0)
	v_readfirstlane_b32 s4, v3
	v_sub_u32_e32 v3, 0, v2
	v_rcp_iflag_f32_e32 v4, v4
	v_add_u32_e32 v5, s4, v1
	v_mul_f32_e32 v4, 0x4f7ffffe, v4
	v_cvt_u32_f32_e32 v4, v4
	v_mul_lo_u32 v1, v3, v4
	v_mul_hi_u32 v1, v4, v1
	v_add_u32_e32 v1, v4, v1
	v_mul_hi_u32 v1, v5, v1
	v_mul_lo_u32 v3, v1, v2
	v_sub_u32_e32 v3, v5, v3
	v_add_u32_e32 v4, 1, v1
	v_cmp_ge_u32_e32 vcc, v3, v2
	s_nop 1
	v_cndmask_b32_e32 v1, v1, v4, vcc
	v_sub_u32_e32 v4, v3, v2
	v_cndmask_b32_e32 v3, v3, v4, vcc
	v_add_u32_e32 v4, 1, v1
	v_cmp_ge_u32_e32 vcc, v3, v2
	v_add_u32_e32 v3, 1, v5
	s_nop 0
	v_cndmask_b32_e32 v1, v1, v4, vcc
	v_mul_lo_u32 v4, v2, v1
	v_add_u32_e32 v2, v4, v2
	v_cmp_ne_u32_e32 vcc, v3, v2
	s_mov_b64 s[4:5], exec
	s_waitcnt lgkmcnt(0)
	v_readfirstlane_b32 s12, v1
	v_readfirstlane_b32 s13, v0
	s_and_b32 s6, s97, 7
	s_lshl_b32 s6, s6, 8
	s_add_u32 s6, s92, s6
	s_addc_u32 s7, s93, 0
	s_add_u32 s6, s6, 0x3800
	s_addc_u32 s7, s7, 0
	s_add_u32 s12, s12, 1
	s_cbranch_vccnz .Lxb4_poll
	buffer_wbl2 sc1
	s_waitcnt vmcnt(0)
	s_lshl_b32 s8, s97, 2
	s_add_u32 s8, s92, s8
	s_addc_u32 s9, s93, 0
	s_add_u32 s8, s8, 0x3800
	s_addc_u32 s9, s9, 0
	s_mov_b64 exec, 0xff
	v_mbcnt_lo_u32_b32 v240, -1, 0
	v_lshlrev_b32_e32 v240, 8, v240
	v_mov_b32_e32 v241, 1
	global_atomic_add v240, v241, s[8:9]
	s_nop 1

; __device__ __forceinline__ unsigned xb_ld(unsigned* p)              { return __hip_atomic_load(p, __ATOMIC_RELAXED, __HIP_MEMORY_SCOPE_AGENT); }
; __device__ __forceinline__ unsigned xb_add(unsigned* p, unsigned v) { return __hip_atomic_fetch_add(p, v, __ATOMIC_RELAXED, __HIP_MEMORY_SCOPE_AGENT); }
; #define XB_SPIN(cond, bar) do { unsigned _sp = 0; while (cond) { __builtin_amdgcn_s_sleep(1); \
;     if ((++_sp & 255u) == 0u) { if (xb_ld(&(bar)[XB_TMO])) break; if (_sp > XB_SPIN_CAP) { atomicAdd(&(bar)[XB_TMO], 1u); break; } } } } while (0)
; __device__ __forceinline__ void xcd_barrier(const XcdBarrier& b) {
;     ...
;             const unsigned tg = og / nx;
;             if (og + 1u != (tg + 1u) * nx) XB_SPIN(xb_ld(&bar[XB_TOP]) < (tg + 1u) * nx, bar);
;             __builtin_amdgcn_fence(__ATOMIC_ACQUIRE, "agent");
;             xb_add(&bar[XB_XGEN(b.x)], 1u);
;             asm volatile("s_waitcnt vmcnt(0)" ::: "memory");
;         } else {
;             XB_SPIN(xb_ld(&bar[XB_XGEN(b.x)]) == gen, bar);
.Lxb4_loop:
	global_load_dword v241, v240, s[6:7] sc1
	s_waitcnt vmcnt(0)
	v_cmp_le_u32_e32 vcc, s12, v241
	s_nop 0
	s_bcnt1_i32_b64 s16, vcc
	s_cmp_ge_u32 s16, s13
	s_cbranch_scc1 .Lxb4_done
	s_add_u32 s17, s17, 1
	s_cmp_lt_u32 s17, 0x4000
	s_cbranch_scc0 .Lxb4_done
	s_sleep 1
	s_branch .Lxb4_loop

; __device__ __forceinline__ unsigned xb_ld(unsigned* p)              { return __hip_atomic_load(p, __ATOMIC_RELAXED, __HIP_MEMORY_SCOPE_AGENT); }
; __device__ __forceinline__ unsigned xb_add(unsigned* p, unsigned v) { return __hip_atomic_fetch_add(p, v, __ATOMIC_RELAXED, __HIP_MEMORY_SCOPE_AGENT); }
; #define XB_SPIN(cond, bar) do { unsigned _sp = 0; while (cond) { __builtin_amdgcn_s_sleep(1); \
;     if ((++_sp & 255u) == 0u) { if (xb_ld(&(bar)[XB_TMO])) break; if (_sp > XB_SPIN_CAP) { atomicAdd(&(bar)[XB_TMO], 1u); break; } } } } while (0)
; __device__ __forceinline__ void xcd_barrier(const XcdBarrier& b) {
;     ...
;         const unsigned old = xb_add(&bar[XB_XSUB(b.x)], 1u);
;         const unsigned gen = old / nloc;
;         if (old + 1u == (gen + 1u) * nloc) {
;             __builtin_amdgcn_fence(__ATOMIC_RELEASE, "agent");
;             asm volatile("s_waitcnt vmcnt(0)" ::: "memory");
;             const unsigned og = xb_add(&bar[XB_TOP], 1u);
;             const unsigned tg = og / nx;
;             if (og + 1u != (tg + 1u) * nx) XB_SPIN(xb_ld(&bar[XB_TOP]) < (tg + 1u) * nx, bar);
;             __builtin_amdgcn_fence(__ATOMIC_ACQUIRE, "agent");
;             xb_add(&bar[XB_XGEN(b.x)], 1u);
;             asm volatile("s_waitcnt vmcnt(0)" ::: "memory");
;         } else {
;             XB_SPIN(xb_ld(&bar[XB_XGEN(b.x)]) == gen, bar);
;             __builtin_amdgcn_fence(__ATOMIC_ACQUIRE, "agent");
;             asm volatile("s_waitcnt vmcnt(0)" ::: "memory");
;         }
.LBB0_626:
	s_or_b64 exec, exec, s[6:7]
	v_cvt_f32_u32_e32 v4, v2
	s_waitcnt vmcnt(0)
	v_readfirstlane_b32 s4, v3
	v_sub_u32_e32 v3, 0, v2
	v_rcp_iflag_f32_e32 v4, v4
	v_add_u32_e32 v5, s4, v1
	v_mul_f32_e32 v4, 0x4f7ffffe, v4
	v_cvt_u32_f32_e32 v4, v4
	v_mul_lo_u32 v1, v3, v4
	v_mul_hi_u32 v1, v4, v1
	v_add_u32_e32 v1, v4, v1
	v_mul_hi_u32 v1, v5, v1
	v_mul_lo_u32 v3, v1, v2
	v_sub_u32_e32 v3, v5, v3
	v_add_u32_e32 v4, 1, v1
	v_cmp_ge_u32_e32 vcc, v3, v2
	s_nop 1
	v_cndmask_b32_e32 v1, v1, v4, vcc
	v_sub_u32_e32 v4, v3, v2
	v_cndmask_b32_e32 v3, v3, v4, vcc
	v_add_u32_e32 v4, 1, v1
	v_cmp_ge_u32_e32 vcc, v3, v2
	v_add_u32_e32 v3, 1, v5
	s_nop 0
	v_cndmask_b32_e32 v1, v1, v4, vcc
	v_mul_lo_u32 v4, v2, v1
	v_add_u32_e32 v2, v4, v2
	v_cmp_ne_u32_e32 vcc, v3, v2
	s_mov_b64 s[4:5], exec
	s_waitcnt lgkmcnt(0)
	v_readfirstlane_b32 s10, v1
	v_readfirstlane_b32 s11, v0
	s_and_b32 s6, s97, 7
	s_lshl_b32 s6, s6, 8
	s_add_u32 s6, s92, s6
	s_addc_u32 s7, s93, 0
	s_add_u32 s6, s6, 0x3800
	s_addc_u32 s7, s7, 0
	s_add_u32 s10, s10, 1
	s_cbranch_vccnz .Lxb5_poll
	buffer_wbl2 sc1
	s_waitcnt vmcnt(0)
	s_lshl_b32 s8, s97, 2
	s_add_u32 s8, s92, s8
	s_addc_u32 s9, s93, 0
	s_add_u32 s8, s8, 0x3800
	s_addc_u32 s9, s9, 0
	s_mov_b64 exec, 0xff
	v_mbcnt_lo_u32_b32 v240, -1, 0
	v_lshlrev_b32_e32 v240, 8, v240
	v_mov_b32_e32 v241, 1
	global_atomic_add v240, v241, s[8:9]
	s_nop 1
.Lxb5_poll:
	s_mov_b64 exec, 0xffff
	v_mbcnt_lo_u32_b32 v240, -1, 0
	v_lshlrev_b32_e32 v240, 2, v240
	s_mov_b32 s13, 0
.Lxb5_loop:
	global_load_dword v241, v240, s[6:7] sc1
	s_waitcnt vmcnt(0)
	v_cmp_le_u32_e32 vcc, s10, v241
	s_nop 0
	s_bcnt1_i32_b64 s12, vcc
	s_cmp_ge_u32 s12, s11
	s_cbranch_scc1 .Lxb5_done
	s_add_u32 s13, s13, 1
	s_cmp_lt_u32 s13, 0x4000
	s_cbranch_scc0 .Lxb5_done
	s_sleep 1
	s_branch .Lxb5_loop

; __device__ __forceinline__ unsigned xb_add(unsigned* p, unsigned v) { return __hip_atomic_fetch_add(p, v, __ATOMIC_RELAXED, __HIP_MEMORY_SCOPE_AGENT); }
; __device__ __forceinline__ void xcd_barrier(const XcdBarrier& b) {
;     ...
;         const unsigned old = xb_add(&bar[XB_XSUB(b.x)], 1u);
;         const unsigned gen = old / nloc;
;         if (old + 1u == (gen + 1u) * nloc) {
;             __builtin_amdgcn_fence(__ATOMIC_RELEASE, "agent");
;             asm volatile("s_waitcnt vmcnt(0)" ::: "memory");
;             const unsigned og = xb_add(&bar[XB_TOP], 1u);
.LBB0_1405:
	s_or_b64 exec, exec, s[6:7]
	v_cvt_f32_u32_e32 v4, v2
	s_waitcnt vmcnt(0)
	v_readfirstlane_b32 s4, v3
	v_sub_u32_e32 v3, 0, v2
	v_rcp_iflag_f32_e32 v4, v4
	v_add_u32_e32 v5, s4, v1
	v_mul_f32_e32 v4, 0x4f7ffffe, v4
	v_cvt_u32_f32_e32 v4, v4
	v_mul_lo_u32 v1, v3, v4
	v_mul_hi_u32 v1, v4, v1
	v_add_u32_e32 v1, v4, v1
	v_mul_hi_u32 v1, v5, v1
	v_mul_lo_u32 v3, v1, v2
	v_sub_u32_e32 v3, v5, v3
	v_add_u32_e32 v4, 1, v1
	v_cmp_ge_u32_e32 vcc, v3, v2
	s_nop 1
	v_cndmask_b32_e32 v1, v1, v4, vcc
	v_sub_u32_e32 v4, v3, v2
	v_cndmask_b32_e32 v3, v3, v4, vcc
	v_add_u32_e32 v4, 1, v1
	v_cmp_ge_u32_e32 vcc, v3, v2
	v_add_u32_e32 v3, 1, v5
	s_nop 0
	v_cndmask_b32_e32 v1, v1, v4, vcc
	v_mul_lo_u32 v4, v2, v1
	v_add_u32_e32 v2, v4, v2
	v_cmp_ne_u32_e32 vcc, v3, v2
	s_mov_b64 s[4:5], exec
	s_waitcnt lgkmcnt(0)
	v_readfirstlane_b32 s10, v1
	v_readfirstlane_b32 s11, v0
	s_and_b32 s6, s54, 7
	s_lshl_b32 s6, s6, 8
	s_add_u32 s6, s52, s6
	s_addc_u32 s7, s53, 0
	s_add_u32 s6, s6, 0x3800
	s_addc_u32 s7, s7, 0
	s_add_u32 s10, s10, 1
	s_cbranch_vccnz .Lxb10_poll
	buffer_wbl2 sc1
	s_waitcnt vmcnt(0)
	s_lshl_b32 s8, s54, 2
	s_add_u32 s8, s52, s8
	s_addc_u32 s9, s53, 0
	s_add_u32 s8, s8, 0x3800
	s_addc_u32 s9, s9, 0
	s_mov_b64 exec, 0xff
	v_mbcnt_lo_u32_b32 v240, -1, 0
	v_lshlrev_b32_e32 v240, 8, v240
	v_mov_b32_e32 v241, 1
	global_atomic_add v240, v241, s[8:9]
	s_nop 1
